# HGRN2 recurrence: per-chunk norm/gate stage issues all 16 ssx + 8 gate LDS reads up front (one LDS round trip instead of 16) on top of v47
# speedup vs baseline: 1.0163x; 1.0040x over previous
.LBB0_1563:
	s_or_b64 exec, exec, s[0:1]
	s_waitcnt lgkmcnt(0)
	s_barrier
	v_pk_mul_f32 v[74:75], v[142:143], v[94:95]
	v_pk_mul_f32 v[72:73], v[140:141], v[92:93]
	v_pk_mul_f32 v[82:83], v[98:99], v[146:147]
	v_pk_mul_f32 v[80:81], v[96:97], v[144:145]
	v_pk_mul_f32 v[78:79], v[102:103], v[150:151]
	v_pk_mul_f32 v[76:77], v[100:101], v[148:149]
	v_pk_mul_f32 v[70:71], v[106:107], v[154:155]
	v_pk_mul_f32 v[68:69], v[104:105], v[152:153]
	v_pk_mul_f32 v[66:67], v[66:67], v[126:127]
	v_pk_mul_f32 v[64:65], v[64:65], v[124:125]
	v_pk_mul_f32 v[62:63], v[130:131], v[62:63]
	v_pk_mul_f32 v[60:61], v[128:129], v[60:61]
	v_pk_mul_f32 v[58:59], v[134:135], v[58:59]
	v_pk_mul_f32 v[56:57], v[132:133], v[56:57]
	v_pk_mul_f32 v[54:55], v[138:139], v[54:55]
	v_pk_mul_f32 v[52:53], v[136:137], v[52:53]
	ds_read_b128 v[108:111], v162 offset:50688
	ds_read_b128 v[112:115], v162 offset:50704
	ds_read_b128 v[116:119], v163 offset:50688
	ds_read_b128 v[120:123], v163 offset:50704
	ds_read_b128 v[140:143], v160 offset:50688
	ds_read_b128 v[144:147], v160 offset:50704
	ds_read_b128 v[164:167], v161 offset:50688
	ds_read_b128 v[180:183], v161 offset:50704
	ds_read_b128 v[184:187], v159 offset:50688
	ds_read_b128 v[188:191], v159 offset:50704
	ds_read_b128 v[228:231], v158 offset:50688
	ds_read_b128 v[232:235], v158 offset:50704
	ds_read_b128 v[236:239], v156 offset:50688
	ds_read_b128 v[240:243], v156 offset:50704
	ds_read_b128 v[244:247], v157 offset:50688
	ds_read_b128 v[248:251], v157 offset:50704
	ds_read_u16 v252, v220 offset:27648
	ds_read_u16 v253, v221 offset:27360
	ds_read_u16 v92, v221 offset:27648
	ds_read_u16 v93, v221 offset:27936
	ds_read_u16 v94, v221 offset:31680
	ds_read_u16 v95, v221 offset:31968
	ds_read_u16 v96, v221 offset:32256
	ds_read_u16 v97, v221 offset:32544
	s_waitcnt lgkmcnt(0)
	v_add_f32_e32 v0, v108, v109
	v_add_f32_e32 v1, v110, v111
	v_add_f32_e32 v0, v0, v1
	v_add_f32_e32 v1, v112, v113
	v_add_f32_e32 v0, v0, v1
	v_add_f32_e32 v1, v114, v115
	v_add_f32_e32 v0, v1, v0
	v_fmamk_f32 v0, v0, 0x3c000000, v222
	v_rsq_f32_e32 v0, v0
	v_lshlrev_b32_e32 v1, 16, v252
	v_mul_f32_e32 v0, v88, v0
	v_mul_f32_e32 v0, v0, v1
	v_bfe_u32 v1, v0, 16, 1
	v_add3_u32 v0, v0, v1, s48
	ds_write_b16_d16_hi v220, v0 offset:36864
	v_add_f32_e32 v0, v116, v117
	v_add_f32_e32 v1, v118, v119
	v_add_f32_e32 v0, v0, v1
	v_add_f32_e32 v1, v120, v121
	v_add_f32_e32 v0, v0, v1
	v_add_f32_e32 v1, v122, v123
	v_add_f32_e32 v0, v1, v0
	v_fmamk_f32 v0, v0, 0x3c000000, v222
	v_rsq_f32_e32 v0, v0
	v_lshlrev_b32_e32 v1, 16, v253
	v_mul_f32_e32 v0, v89, v0
	v_mul_f32_e32 v0, v0, v1
	v_bfe_u32 v1, v0, 16, 1
	v_add3_u32 v0, v0, v1, s48
	ds_write_b16_d16_hi v221, v0 offset:36576
	v_add_f32_e32 v0, v140, v141
	v_add_f32_e32 v1, v142, v143
	v_add_f32_e32 v0, v0, v1
	v_add_f32_e32 v1, v144, v145
	v_add_f32_e32 v0, v0, v1
	v_add_f32_e32 v1, v146, v147
	v_add_f32_e32 v0, v1, v0
	v_fmamk_f32 v0, v0, 0x3c000000, v222
	v_rsq_f32_e32 v0, v0
	v_lshlrev_b32_e32 v1, 16, v92
	v_mul_f32_e32 v0, v90, v0
	v_mul_f32_e32 v0, v0, v1
	v_bfe_u32 v1, v0, 16, 1
	v_add3_u32 v0, v0, v1, s48
	ds_write_b16_d16_hi v221, v0 offset:36864
	v_add_f32_e32 v0, v164, v165
	v_add_f32_e32 v1, v166, v167
	v_add_f32_e32 v0, v0, v1
	v_add_f32_e32 v1, v180, v181
	v_add_f32_e32 v0, v0, v1
	v_add_f32_e32 v1, v182, v183
	v_add_f32_e32 v0, v1, v0
	v_fmamk_f32 v0, v0, 0x3c000000, v222
	v_rsq_f32_e32 v0, v0
	v_lshlrev_b32_e32 v1, 16, v93
	v_mul_f32_e32 v0, v91, v0
	v_mul_f32_e32 v0, v0, v1
	v_bfe_u32 v1, v0, 16, 1
	v_add3_u32 v0, v0, v1, s48
	ds_write_b16_d16_hi v221, v0 offset:37152
	v_add_f32_e32 v0, v184, v185
	v_add_f32_e32 v1, v186, v187
	v_add_f32_e32 v0, v0, v1
	v_add_f32_e32 v1, v188, v189
	v_add_f32_e32 v0, v0, v1
	v_add_f32_e32 v1, v190, v191
	v_add_f32_e32 v0, v1, v0
	v_fmamk_f32 v0, v0, 0x3c000000, v222
	v_rsq_f32_e32 v0, v0
	v_lshlrev_b32_e32 v1, 16, v94
	v_mul_f32_e32 v0, v84, v0
	v_mul_f32_e32 v0, v0, v1
	v_bfe_u32 v1, v0, 16, 1
	v_add3_u32 v0, v0, v1, s48
	ds_write_b16_d16_hi v221, v0 offset:40896
	v_add_f32_e32 v0, v228, v229
	v_add_f32_e32 v1, v230, v231
	v_add_f32_e32 v0, v0, v1
	v_add_f32_e32 v1, v232, v233
	v_add_f32_e32 v0, v0, v1
	v_add_f32_e32 v1, v234, v235
	v_add_f32_e32 v0, v1, v0
	v_fmamk_f32 v0, v0, 0x3c000000, v222
	v_rsq_f32_e32 v0, v0
	v_lshlrev_b32_e32 v1, 16, v95
	v_mul_f32_e32 v0, v85, v0
	v_mul_f32_e32 v0, v0, v1
	v_bfe_u32 v1, v0, 16, 1
	v_add3_u32 v0, v0, v1, s48
	ds_write_b16_d16_hi v221, v0 offset:41184
	v_add_f32_e32 v0, v236, v237
	v_add_f32_e32 v1, v238, v239
	v_add_f32_e32 v0, v0, v1
	v_add_f32_e32 v1, v240, v241
	v_add_f32_e32 v0, v0, v1
	v_add_f32_e32 v1, v242, v243
	v_add_f32_e32 v0, v1, v0
	v_fmamk_f32 v0, v0, 0x3c000000, v222
	v_rsq_f32_e32 v0, v0
	v_lshlrev_b32_e32 v1, 16, v96
	v_mul_f32_e32 v0, v86, v0
	v_mul_f32_e32 v0, v0, v1
	v_bfe_u32 v1, v0, 16, 1
	v_add3_u32 v0, v0, v1, s48
	ds_write_b16_d16_hi v221, v0 offset:41472
	v_add_f32_e32 v0, v244, v245
	v_add_f32_e32 v1, v246, v247
	v_add_f32_e32 v0, v0, v1
	v_add_f32_e32 v1, v248, v249
	v_add_f32_e32 v0, v0, v1
	v_add_f32_e32 v1, v250, v251
	v_add_f32_e32 v0, v1, v0
	v_fmamk_f32 v0, v0, 0x3c000000, v222
	v_rsq_f32_e32 v0, v0
	v_lshlrev_b32_e32 v1, 16, v97
	v_mul_f32_e32 v0, v87, v0
	v_mul_f32_e32 v0, v0, v1
	v_bfe_u32 v1, v0, 16, 1
	v_add3_u32 v0, v0, v1, s48
	ds_write_b16_d16_hi v221, v0 offset:41760

.LBB0_1579:
	s_or_b64 exec, exec, s[0:1]
	v_pk_mul_f32 v[78:79], v[102:103], v[162:163]
	s_waitcnt lgkmcnt(0)
	s_barrier
	v_add_u32_e32 v162, 0, v208
	v_pk_mul_f32 v[74:75], v[154:155], v[94:95]
	v_pk_mul_f32 v[72:73], v[152:153], v[92:93]
	v_pk_mul_f32 v[82:83], v[98:99], v[158:159]
	v_pk_mul_f32 v[80:81], v[96:97], v[156:157]
	v_add_u32_e32 v163, 0, v209
	v_pk_mul_f32 v[76:77], v[100:101], v[160:161]
	v_add_u32_e32 v160, 0, v210
	v_add_u32_e32 v161, 0, v211
	v_add_u32_e32 v159, 0, v212
	v_add_u32_e32 v158, 0, v213
	v_add_u32_e32 v156, 0, v214
	v_add_u32_e32 v157, 0, v215
	v_pk_mul_f32 v[70:71], v[106:107], v[166:167]
	v_pk_mul_f32 v[68:69], v[104:105], v[164:165]
	v_pk_mul_f32 v[66:67], v[66:67], v[138:139]
	v_pk_mul_f32 v[64:65], v[64:65], v[136:137]
	v_pk_mul_f32 v[62:63], v[142:143], v[62:63]
	v_pk_mul_f32 v[60:61], v[140:141], v[60:61]
	v_pk_mul_f32 v[58:59], v[146:147], v[58:59]
	v_pk_mul_f32 v[56:57], v[144:145], v[56:57]
	v_pk_mul_f32 v[54:55], v[150:151], v[54:55]
	v_pk_mul_f32 v[52:53], v[148:149], v[52:53]
	s_cmp_gt_u32 s3, 64
	ds_read_b128 v[108:111], v162 offset:50688
	ds_read_b128 v[112:115], v162 offset:50704
	ds_read_b128 v[116:119], v163 offset:50688
	ds_read_b128 v[120:123], v163 offset:50704
	ds_read_b128 v[124:127], v160 offset:50688
	ds_read_b128 v[128:131], v160 offset:50704
	ds_read_b128 v[132:135], v161 offset:50688
	ds_read_b128 v[152:155], v161 offset:50704
	ds_read_b128 v[180:183], v159 offset:50688
	ds_read_b128 v[184:187], v159 offset:50704
	ds_read_b128 v[188:191], v158 offset:50688
	ds_read_b128 v[228:231], v158 offset:50704
	ds_read_b128 v[232:235], v156 offset:50688
	ds_read_b128 v[236:239], v156 offset:50704
	ds_read_b128 v[240:243], v157 offset:50688
	ds_read_b128 v[244:247], v157 offset:50704
	ds_read_u16 v102, v220 offset:27648
	ds_read_u16 v103, v221 offset:27360
	ds_read_u16 v252, v221 offset:27648
	ds_read_u16 v253, v221 offset:27936
	ds_read_u16 v92, v221 offset:31680
	ds_read_u16 v93, v221 offset:31968
	ds_read_u16 v94, v221 offset:32256
	ds_read_u16 v95, v221 offset:32544
	s_waitcnt lgkmcnt(0)
	v_add_f32_e32 v0, v108, v109
	v_add_f32_e32 v1, v110, v111
	v_add_f32_e32 v0, v0, v1
	v_add_f32_e32 v1, v112, v113
	v_add_f32_e32 v0, v0, v1
	v_add_f32_e32 v1, v114, v115
	v_add_f32_e32 v0, v1, v0
	v_fmamk_f32 v0, v0, 0x3c000000, v222
	v_rsq_f32_e32 v0, v0
	v_lshlrev_b32_e32 v1, 16, v102
	v_mul_f32_e32 v0, v88, v0
	v_mul_f32_e32 v0, v0, v1
	v_bfe_u32 v1, v0, 16, 1
	v_add3_u32 v0, v0, v1, s48
	ds_write_b16_d16_hi v220, v0 offset:36864
	v_add_f32_e32 v0, v116, v117
	v_add_f32_e32 v1, v118, v119
	v_add_f32_e32 v0, v0, v1
	v_add_f32_e32 v1, v120, v121
	v_add_f32_e32 v0, v0, v1
	v_add_f32_e32 v1, v122, v123
	v_add_f32_e32 v0, v1, v0
	v_fmamk_f32 v0, v0, 0x3c000000, v222
	v_rsq_f32_e32 v0, v0
	v_lshlrev_b32_e32 v1, 16, v103
	v_mul_f32_e32 v0, v89, v0
	v_mul_f32_e32 v0, v0, v1
	v_bfe_u32 v1, v0, 16, 1
	v_add3_u32 v0, v0, v1, s48
	ds_write_b16_d16_hi v221, v0 offset:36576
	v_add_f32_e32 v0, v124, v125
	v_add_f32_e32 v1, v126, v127
	v_add_f32_e32 v0, v0, v1
	v_add_f32_e32 v1, v128, v129
	v_add_f32_e32 v0, v0, v1
	v_add_f32_e32 v1, v130, v131
	v_add_f32_e32 v0, v1, v0
	v_fmamk_f32 v0, v0, 0x3c000000, v222
	v_rsq_f32_e32 v0, v0
	v_lshlrev_b32_e32 v1, 16, v252
	v_mul_f32_e32 v0, v90, v0
	v_mul_f32_e32 v0, v0, v1
	v_bfe_u32 v1, v0, 16, 1
	v_add3_u32 v0, v0, v1, s48
	ds_write_b16_d16_hi v221, v0 offset:36864
	v_add_f32_e32 v0, v132, v133
	v_add_f32_e32 v1, v134, v135
	v_add_f32_e32 v0, v0, v1
	v_add_f32_e32 v1, v152, v153
	v_add_f32_e32 v0, v0, v1
	v_add_f32_e32 v1, v154, v155
	v_add_f32_e32 v0, v1, v0
	v_fmamk_f32 v0, v0, 0x3c000000, v222
	v_rsq_f32_e32 v0, v0
	v_lshlrev_b32_e32 v1, 16, v253
	v_mul_f32_e32 v0, v91, v0
	v_mul_f32_e32 v0, v0, v1
	v_bfe_u32 v1, v0, 16, 1
	v_add3_u32 v0, v0, v1, s48
	ds_write_b16_d16_hi v221, v0 offset:37152
	v_add_f32_e32 v0, v180, v181
	v_add_f32_e32 v1, v182, v183
	v_add_f32_e32 v0, v0, v1
	v_add_f32_e32 v1, v184, v185
	v_add_f32_e32 v0, v0, v1
	v_add_f32_e32 v1, v186, v187
	v_add_f32_e32 v0, v1, v0
	v_fmamk_f32 v0, v0, 0x3c000000, v222
	v_rsq_f32_e32 v0, v0
	v_lshlrev_b32_e32 v1, 16, v92
	v_mul_f32_e32 v0, v84, v0
	v_mul_f32_e32 v0, v0, v1
	v_bfe_u32 v1, v0, 16, 1
	v_add3_u32 v0, v0, v1, s48
	ds_write_b16_d16_hi v221, v0 offset:40896
	v_add_f32_e32 v0, v188, v189
	v_add_f32_e32 v1, v190, v191
	v_add_f32_e32 v0, v0, v1
	v_add_f32_e32 v1, v228, v229
	v_add_f32_e32 v0, v0, v1
	v_add_f32_e32 v1, v230, v231
	v_add_f32_e32 v0, v1, v0
	v_fmamk_f32 v0, v0, 0x3c000000, v222
	v_rsq_f32_e32 v0, v0
	v_lshlrev_b32_e32 v1, 16, v93
	v_mul_f32_e32 v0, v85, v0
	v_mul_f32_e32 v0, v0, v1
	v_bfe_u32 v1, v0, 16, 1
	v_add3_u32 v0, v0, v1, s48
	ds_write_b16_d16_hi v221, v0 offset:41184
	v_add_f32_e32 v0, v232, v233
	v_add_f32_e32 v1, v234, v235
	v_add_f32_e32 v0, v0, v1
	v_add_f32_e32 v1, v236, v237
	v_add_f32_e32 v0, v0, v1
	v_add_f32_e32 v1, v238, v239
	v_add_f32_e32 v0, v1, v0
	v_fmamk_f32 v0, v0, 0x3c000000, v222
	v_rsq_f32_e32 v0, v0
	v_lshlrev_b32_e32 v1, 16, v94
	v_mul_f32_e32 v0, v86, v0
	v_mul_f32_e32 v0, v0, v1
	v_bfe_u32 v1, v0, 16, 1
	v_add3_u32 v0, v0, v1, s48
	ds_write_b16_d16_hi v221, v0 offset:41472
	v_add_f32_e32 v0, v240, v241
	v_add_f32_e32 v1, v242, v243
	v_add_f32_e32 v0, v0, v1
	v_add_f32_e32 v1, v244, v245
	v_add_f32_e32 v0, v0, v1
	v_add_f32_e32 v1, v246, v247
	v_add_f32_e32 v0, v1, v0
	v_fmamk_f32 v0, v0, 0x3c000000, v222
	v_rsq_f32_e32 v0, v0
	v_lshlrev_b32_e32 v1, 16, v95
	v_mul_f32_e32 v0, v87, v0
	v_mul_f32_e32 v0, v0, v1
	v_bfe_u32 v1, v0, 16, 1
	v_add3_u32 v0, v0, v1, s48
	ds_write_b16_d16_hi v221, v0 offset:41760
	s_cbranch_scc1 .LBB0_1564
	s_waitcnt vmcnt(0)
	v_add_f32_dpp v86, v47, v47 row_shr:1 row_mask:0xf bank_mask:0xf bound_ctrl:1
	v_add_f32_dpp v88, v49, v49 row_shr:1 row_mask:0xf bank_mask:0xf bound_ctrl:1
	v_add_f32_dpp v0, v44, v44 row_shr:1 row_mask:0xf bank_mask:0xf bound_ctrl:1
	v_add_f32_dpp v86, v86, v86 row_shr:2 row_mask:0xf bank_mask:0xf bound_ctrl:1
	v_add_f32_dpp v88, v88, v88 row_shr:2 row_mask:0xf bank_mask:0xf bound_ctrl:1
	v_add_f32_dpp v3, v45, v45 row_shr:1 row_mask:0xf bank_mask:0xf bound_ctrl:1
	v_add_f32_dpp v86, v86, v86 row_shr:4 row_mask:0xf bank_mask:0xf bound_ctrl:1
	v_add_f32_dpp v88, v88, v88 row_shr:4 row_mask:0xf bank_mask:0xf bound_ctrl:1
	v_add_f32_dpp v84, v46, v46 row_shr:1 row_mask:0xf bank_mask:0xf bound_ctrl:1
	v_add_f32_dpp v95, v86, v86 row_shr:8 row_mask:0xf bank_mask:0xf bound_ctrl:1
	v_add_f32_dpp v86, v48, v48 row_shr:1 row_mask:0xf bank_mask:0xf bound_ctrl:1
	v_add_f32_dpp v93, v88, v88 row_shr:8 row_mask:0xf bank_mask:0xf bound_ctrl:1
	v_add_f32_dpp v88, v50, v50 row_shr:1 row_mask:0xf bank_mask:0xf bound_ctrl:1
	v_add_f32_dpp v90, v51, v51 row_shr:1 row_mask:0xf bank_mask:0xf bound_ctrl:1
	v_add_f32_dpp v0, v0, v0 row_shr:2 row_mask:0xf bank_mask:0xf bound_ctrl:1
	v_add_f32_dpp v3, v3, v3 row_shr:2 row_mask:0xf bank_mask:0xf bound_ctrl:1
	v_add_f32_dpp v84, v84, v84 row_shr:2 row_mask:0xf bank_mask:0xf bound_ctrl:1
	v_add_f32_dpp v86, v86, v86 row_shr:2 row_mask:0xf bank_mask:0xf bound_ctrl:1
	v_add_f32_dpp v88, v88, v88 row_shr:2 row_mask:0xf bank_mask:0xf bound_ctrl:1
	v_add_f32_dpp v90, v90, v90 row_shr:2 row_mask:0xf bank_mask:0xf bound_ctrl:1
	v_add_f32_dpp v0, v0, v0 row_shr:4 row_mask:0xf bank_mask:0xf bound_ctrl:1
	v_add_f32_dpp v3, v3, v3 row_shr:4 row_mask:0xf bank_mask:0xf bound_ctrl:1
	v_add_f32_dpp v84, v84, v84 row_shr:4 row_mask:0xf bank_mask:0xf bound_ctrl:1
	v_add_f32_dpp v86, v86, v86 row_shr:4 row_mask:0xf bank_mask:0xf bound_ctrl:1
	v_add_f32_dpp v88, v88, v88 row_shr:4 row_mask:0xf bank_mask:0xf bound_ctrl:1
	v_add_f32_dpp v90, v90, v90 row_shr:4 row_mask:0xf bank_mask:0xf bound_ctrl:1
	s_waitcnt lgkmcnt(0)
	s_barrier
	s_cmp_lg_u32 s3, 1
	v_add_f32_dpp v0, v0, v0 row_shr:8 row_mask:0xf bank_mask:0xf bound_ctrl:1
	v_mov_b32_e32 v1, 0
	v_add_f32_dpp v3, v3, v3 row_shr:8 row_mask:0xf bank_mask:0xf bound_ctrl:1
	v_mov_b32_e32 v97, 0
	v_add_f32_dpp v84, v84, v84 row_shr:8 row_mask:0xf bank_mask:0xf bound_ctrl:1
	v_mov_b32_e32 v85, 0
	v_mov_b32_e32 v96, 0
	v_add_f32_dpp v86, v86, v86 row_shr:8 row_mask:0xf bank_mask:0xf bound_ctrl:1
	v_mov_b32_e32 v87, 0
	v_mov_b32_e32 v94, 0
	v_add_f32_dpp v88, v88, v88 row_shr:8 row_mask:0xf bank_mask:0xf bound_ctrl:1
	v_mov_b32_e32 v89, 0
	v_add_f32_dpp v91, v90, v90 row_shr:8 row_mask:0xf bank_mask:0xf bound_ctrl:1
	v_mov_b32_e32 v92, 0
	s_cselect_b64 s[0:1], -1, 0
	v_mov_b32_dpp v1, v0 row_bcast:15 row_mask:0xa bank_mask:0xf
	v_mov_b32_dpp v97, v3 row_bcast:15 row_mask:0xa bank_mask:0xf
	v_mov_b32_dpp v85, v84 row_bcast:15 row_mask:0xa bank_mask:0xf
	v_mov_b32_dpp v96, v95 row_bcast:15 row_mask:0xa bank_mask:0xf
	v_mov_b32_dpp v87, v86 row_bcast:15 row_mask:0xa bank_mask:0xf
	v_mov_b32_dpp v94, v93 row_bcast:15 row_mask:0xa bank_mask:0xf
	v_mov_b32_dpp v89, v88 row_bcast:15 row_mask:0xa bank_mask:0xf
	v_mov_b32_dpp v92, v91 row_bcast:15 row_mask:0xa bank_mask:0xf
	s_or_b64 s[50:51], s[52:53], s[0:1]
	s_and_saveexec_b64 s[0:1], s[50:51]
	s_cbranch_execz .LBB0_1582
	v_cndmask_b32_e64 v98, v218, v216, s[16:17]
	v_ashrrev_i32_e32 v99, 31, v98
	v_lshlrev_b64 v[98:99], 11, v[98:99]
	v_add_u32_e32 v90, v200, v172
	v_lshl_add_u64 v[102:103], v[174:175], 0, v[98:99]
	ds_read_b128 v[98:101], v90 offset:36864
	s_waitcnt lgkmcnt(0)
	global_store_dwordx4 v[102:103], v[98:101], off

.LBB0_1796:
	s_or_b64 exec, exec, s[0:1]
	s_waitcnt lgkmcnt(0)
	s_barrier
	v_pk_mul_f32 v[74:75], v[142:143], v[94:95]
	v_pk_mul_f32 v[72:73], v[140:141], v[92:93]
	v_pk_mul_f32 v[82:83], v[98:99], v[146:147]
	v_pk_mul_f32 v[80:81], v[96:97], v[144:145]
	v_pk_mul_f32 v[78:79], v[102:103], v[150:151]
	v_pk_mul_f32 v[76:77], v[100:101], v[148:149]
	v_pk_mul_f32 v[70:71], v[106:107], v[154:155]
	v_pk_mul_f32 v[68:69], v[104:105], v[152:153]
	v_pk_mul_f32 v[66:67], v[66:67], v[126:127]
	v_pk_mul_f32 v[64:65], v[64:65], v[124:125]
	v_pk_mul_f32 v[62:63], v[130:131], v[62:63]
	v_pk_mul_f32 v[60:61], v[128:129], v[60:61]
	v_pk_mul_f32 v[58:59], v[134:135], v[58:59]
	v_pk_mul_f32 v[56:57], v[132:133], v[56:57]
	v_pk_mul_f32 v[54:55], v[138:139], v[54:55]
	v_pk_mul_f32 v[52:53], v[136:137], v[52:53]
	ds_read_b128 v[108:111], v162 offset:50688
	ds_read_b128 v[112:115], v162 offset:50704
	ds_read_b128 v[116:119], v163 offset:50688
	ds_read_b128 v[120:123], v163 offset:50704
	ds_read_b128 v[140:143], v160 offset:50688
	ds_read_b128 v[144:147], v160 offset:50704
	ds_read_b128 v[164:167], v161 offset:50688
	ds_read_b128 v[180:183], v161 offset:50704
	ds_read_b128 v[184:187], v159 offset:50688
	ds_read_b128 v[188:191], v159 offset:50704
	ds_read_b128 v[216:219], v158 offset:50688
	ds_read_b128 v[228:231], v158 offset:50704
	ds_read_b128 v[232:235], v156 offset:50688
	ds_read_b128 v[236:239], v156 offset:50704
	ds_read_b128 v[240:243], v157 offset:50688
	ds_read_b128 v[244:247], v157 offset:50704
	ds_read_u16 v215, v213 offset:27648
	ds_read_u16 v220, v214 offset:27360
	ds_read_u16 v221, v214 offset:27648
	ds_read_u16 v252, v214 offset:27936
	ds_read_u16 v253, v214 offset:31680
	ds_read_u16 v92, v214 offset:31968
	ds_read_u16 v93, v214 offset:32256
	ds_read_u16 v94, v214 offset:32544
	s_waitcnt lgkmcnt(0)
	v_add_f32_e32 v0, v108, v109
	v_add_f32_e32 v1, v110, v111
	v_add_f32_e32 v0, v0, v1
	v_add_f32_e32 v1, v112, v113
	v_add_f32_e32 v0, v0, v1
	v_add_f32_e32 v1, v114, v115
	v_add_f32_e32 v0, v1, v0
	v_fmamk_f32 v0, v0, 0x3c000000, v222
	v_rsq_f32_e32 v0, v0
	v_lshlrev_b32_e32 v1, 16, v215
	v_mul_f32_e32 v0, v88, v0
	v_mul_f32_e32 v0, v0, v1
	v_bfe_u32 v1, v0, 16, 1
	v_add3_u32 v0, v0, v1, s48
	ds_write_b16_d16_hi v213, v0 offset:36864
	v_add_f32_e32 v0, v116, v117
	v_add_f32_e32 v1, v118, v119
	v_add_f32_e32 v0, v0, v1
	v_add_f32_e32 v1, v120, v121
	v_add_f32_e32 v0, v0, v1
	v_add_f32_e32 v1, v122, v123
	v_add_f32_e32 v0, v1, v0
	v_fmamk_f32 v0, v0, 0x3c000000, v222
	v_rsq_f32_e32 v0, v0
	v_lshlrev_b32_e32 v1, 16, v220
	v_mul_f32_e32 v0, v89, v0
	v_mul_f32_e32 v0, v0, v1
	v_bfe_u32 v1, v0, 16, 1
	v_add3_u32 v0, v0, v1, s48
	ds_write_b16_d16_hi v214, v0 offset:36576
	v_add_f32_e32 v0, v140, v141
	v_add_f32_e32 v1, v142, v143
	v_add_f32_e32 v0, v0, v1
	v_add_f32_e32 v1, v144, v145
	v_add_f32_e32 v0, v0, v1
	v_add_f32_e32 v1, v146, v147
	v_add_f32_e32 v0, v1, v0
	v_fmamk_f32 v0, v0, 0x3c000000, v222
	v_rsq_f32_e32 v0, v0
	v_lshlrev_b32_e32 v1, 16, v221
	v_mul_f32_e32 v0, v90, v0
	v_mul_f32_e32 v0, v0, v1
	v_bfe_u32 v1, v0, 16, 1
	v_add3_u32 v0, v0, v1, s48
	ds_write_b16_d16_hi v214, v0 offset:36864
	v_add_f32_e32 v0, v164, v165
	v_add_f32_e32 v1, v166, v167
	v_add_f32_e32 v0, v0, v1
	v_add_f32_e32 v1, v180, v181
	v_add_f32_e32 v0, v0, v1
	v_add_f32_e32 v1, v182, v183
	v_add_f32_e32 v0, v1, v0
	v_fmamk_f32 v0, v0, 0x3c000000, v222
	v_rsq_f32_e32 v0, v0
	v_lshlrev_b32_e32 v1, 16, v252
	v_mul_f32_e32 v0, v91, v0
	v_mul_f32_e32 v0, v0, v1
	v_bfe_u32 v1, v0, 16, 1
	v_add3_u32 v0, v0, v1, s48
	ds_write_b16_d16_hi v214, v0 offset:37152
	v_add_f32_e32 v0, v184, v185
	v_add_f32_e32 v1, v186, v187
	v_add_f32_e32 v0, v0, v1
	v_add_f32_e32 v1, v188, v189
	v_add_f32_e32 v0, v0, v1
	v_add_f32_e32 v1, v190, v191
	v_add_f32_e32 v0, v1, v0
	v_fmamk_f32 v0, v0, 0x3c000000, v222
	v_rsq_f32_e32 v0, v0
	v_lshlrev_b32_e32 v1, 16, v253
	v_mul_f32_e32 v0, v84, v0
	v_mul_f32_e32 v0, v0, v1
	v_bfe_u32 v1, v0, 16, 1
	v_add3_u32 v0, v0, v1, s48
	ds_write_b16_d16_hi v214, v0 offset:40896
	v_add_f32_e32 v0, v216, v217
	v_add_f32_e32 v1, v218, v219
	v_add_f32_e32 v0, v0, v1
	v_add_f32_e32 v1, v228, v229
	v_add_f32_e32 v0, v0, v1
	v_add_f32_e32 v1, v230, v231
	v_add_f32_e32 v0, v1, v0
	v_fmamk_f32 v0, v0, 0x3c000000, v222
	v_rsq_f32_e32 v0, v0
	v_lshlrev_b32_e32 v1, 16, v92
	v_mul_f32_e32 v0, v85, v0
	v_mul_f32_e32 v0, v0, v1
	v_bfe_u32 v1, v0, 16, 1
	v_add3_u32 v0, v0, v1, s48
	ds_write_b16_d16_hi v214, v0 offset:41184
	v_add_f32_e32 v0, v232, v233
	v_add_f32_e32 v1, v234, v235
	v_add_f32_e32 v0, v0, v1
	v_add_f32_e32 v1, v236, v237
	v_add_f32_e32 v0, v0, v1
	v_add_f32_e32 v1, v238, v239
	v_add_f32_e32 v0, v1, v0
	v_fmamk_f32 v0, v0, 0x3c000000, v222
	v_rsq_f32_e32 v0, v0
	v_lshlrev_b32_e32 v1, 16, v93
	v_mul_f32_e32 v0, v86, v0
	v_mul_f32_e32 v0, v0, v1
	v_bfe_u32 v1, v0, 16, 1
	v_add3_u32 v0, v0, v1, s48
	ds_write_b16_d16_hi v214, v0 offset:41472
	v_add_f32_e32 v0, v240, v241
	v_add_f32_e32 v1, v242, v243
	v_add_f32_e32 v0, v0, v1
	v_add_f32_e32 v1, v244, v245
	v_add_f32_e32 v0, v0, v1
	v_add_f32_e32 v1, v246, v247
	v_add_f32_e32 v0, v1, v0
	v_fmamk_f32 v0, v0, 0x3c000000, v222
	v_rsq_f32_e32 v0, v0
	v_lshlrev_b32_e32 v1, 16, v94
	v_mul_f32_e32 v0, v87, v0
	v_mul_f32_e32 v0, v0, v1
	v_bfe_u32 v1, v0, 16, 1
	v_add3_u32 v0, v0, v1, s48
	ds_write_b16_d16_hi v214, v0 offset:41760

.LBB0_1812:
	s_or_b64 exec, exec, s[0:1]
	v_pk_mul_f32 v[78:79], v[102:103], v[162:163]
	s_waitcnt lgkmcnt(0)
	s_barrier
	v_add_u32_e32 v162, 0, v202
	v_pk_mul_f32 v[74:75], v[154:155], v[94:95]
	v_pk_mul_f32 v[72:73], v[152:153], v[92:93]
	v_pk_mul_f32 v[82:83], v[98:99], v[158:159]
	v_pk_mul_f32 v[80:81], v[96:97], v[156:157]
	v_add_u32_e32 v163, 0, v203
	v_pk_mul_f32 v[76:77], v[100:101], v[160:161]
	v_add_u32_e32 v160, 0, v204
	v_add_u32_e32 v161, 0, v205
	v_add_u32_e32 v159, 0, v206
	v_add_u32_e32 v158, 0, v207
	v_add_u32_e32 v156, 0, v208
	v_add_u32_e32 v157, 0, v209
	v_pk_mul_f32 v[70:71], v[106:107], v[166:167]
	v_pk_mul_f32 v[68:69], v[104:105], v[164:165]
	v_pk_mul_f32 v[66:67], v[66:67], v[138:139]
	v_pk_mul_f32 v[64:65], v[64:65], v[136:137]
	v_pk_mul_f32 v[62:63], v[142:143], v[62:63]
	v_pk_mul_f32 v[60:61], v[140:141], v[60:61]
	v_pk_mul_f32 v[58:59], v[146:147], v[58:59]
	v_pk_mul_f32 v[56:57], v[144:145], v[56:57]
	v_pk_mul_f32 v[54:55], v[150:151], v[54:55]
	v_pk_mul_f32 v[52:53], v[148:149], v[52:53]
	s_cmp_gt_u32 s3, 64
	ds_read_b128 v[108:111], v162 offset:50688
	ds_read_b128 v[112:115], v162 offset:50704
	ds_read_b128 v[116:119], v163 offset:50688
	ds_read_b128 v[120:123], v163 offset:50704
	ds_read_b128 v[124:127], v160 offset:50688
	ds_read_b128 v[128:131], v160 offset:50704
	ds_read_b128 v[132:135], v161 offset:50688
	ds_read_b128 v[152:155], v161 offset:50704
	ds_read_b128 v[180:183], v159 offset:50688
	ds_read_b128 v[184:187], v159 offset:50704
	ds_read_b128 v[188:191], v158 offset:50688
	ds_read_b128 v[216:219], v158 offset:50704
	ds_read_b128 v[228:231], v156 offset:50688
	ds_read_b128 v[232:235], v156 offset:50704
	ds_read_b128 v[236:239], v157 offset:50688
	ds_read_b128 v[240:243], v157 offset:50704
	ds_read_u16 v102, v213 offset:27648
	ds_read_u16 v103, v214 offset:27360
	ds_read_u16 v215, v214 offset:27648
	ds_read_u16 v220, v214 offset:27936
	ds_read_u16 v221, v214 offset:31680
	ds_read_u16 v252, v214 offset:31968
	ds_read_u16 v253, v214 offset:32256
	ds_read_u16 v92, v214 offset:32544
	s_waitcnt lgkmcnt(0)
	v_add_f32_e32 v0, v108, v109
	v_add_f32_e32 v1, v110, v111
	v_add_f32_e32 v0, v0, v1
	v_add_f32_e32 v1, v112, v113
	v_add_f32_e32 v0, v0, v1
	v_add_f32_e32 v1, v114, v115
	v_add_f32_e32 v0, v1, v0
	v_fmamk_f32 v0, v0, 0x3c000000, v222
	v_rsq_f32_e32 v0, v0
	v_lshlrev_b32_e32 v1, 16, v102
	v_mul_f32_e32 v0, v88, v0
	v_mul_f32_e32 v0, v0, v1
	v_bfe_u32 v1, v0, 16, 1
	v_add3_u32 v0, v0, v1, s48
	ds_write_b16_d16_hi v213, v0 offset:36864
	v_add_f32_e32 v0, v116, v117
	v_add_f32_e32 v1, v118, v119
	v_add_f32_e32 v0, v0, v1
	v_add_f32_e32 v1, v120, v121
	v_add_f32_e32 v0, v0, v1
	v_add_f32_e32 v1, v122, v123
	v_add_f32_e32 v0, v1, v0
	v_fmamk_f32 v0, v0, 0x3c000000, v222
	v_rsq_f32_e32 v0, v0
	v_lshlrev_b32_e32 v1, 16, v103
	v_mul_f32_e32 v0, v89, v0
	v_mul_f32_e32 v0, v0, v1
	v_bfe_u32 v1, v0, 16, 1
	v_add3_u32 v0, v0, v1, s48
	ds_write_b16_d16_hi v214, v0 offset:36576
	v_add_f32_e32 v0, v124, v125
	v_add_f32_e32 v1, v126, v127
	v_add_f32_e32 v0, v0, v1
	v_add_f32_e32 v1, v128, v129
	v_add_f32_e32 v0, v0, v1
	v_add_f32_e32 v1, v130, v131
	v_add_f32_e32 v0, v1, v0
	v_fmamk_f32 v0, v0, 0x3c000000, v222
	v_rsq_f32_e32 v0, v0
	v_lshlrev_b32_e32 v1, 16, v215
	v_mul_f32_e32 v0, v90, v0
	v_mul_f32_e32 v0, v0, v1
	v_bfe_u32 v1, v0, 16, 1
	v_add3_u32 v0, v0, v1, s48
	ds_write_b16_d16_hi v214, v0 offset:36864
	v_add_f32_e32 v0, v132, v133
	v_add_f32_e32 v1, v134, v135
	v_add_f32_e32 v0, v0, v1
	v_add_f32_e32 v1, v152, v153
	v_add_f32_e32 v0, v0, v1
	v_add_f32_e32 v1, v154, v155
	v_add_f32_e32 v0, v1, v0
	v_fmamk_f32 v0, v0, 0x3c000000, v222
	v_rsq_f32_e32 v0, v0
	v_lshlrev_b32_e32 v1, 16, v220
	v_mul_f32_e32 v0, v91, v0
	v_mul_f32_e32 v0, v0, v1
	v_bfe_u32 v1, v0, 16, 1
	v_add3_u32 v0, v0, v1, s48
	ds_write_b16_d16_hi v214, v0 offset:37152
	v_add_f32_e32 v0, v180, v181
	v_add_f32_e32 v1, v182, v183
	v_add_f32_e32 v0, v0, v1
	v_add_f32_e32 v1, v184, v185
	v_add_f32_e32 v0, v0, v1
	v_add_f32_e32 v1, v186, v187
	v_add_f32_e32 v0, v1, v0
	v_fmamk_f32 v0, v0, 0x3c000000, v222
	v_rsq_f32_e32 v0, v0
	v_lshlrev_b32_e32 v1, 16, v221
	v_mul_f32_e32 v0, v84, v0
	v_mul_f32_e32 v0, v0, v1
	v_bfe_u32 v1, v0, 16, 1
	v_add3_u32 v0, v0, v1, s48
	ds_write_b16_d16_hi v214, v0 offset:40896
	v_add_f32_e32 v0, v188, v189
	v_add_f32_e32 v1, v190, v191
	v_add_f32_e32 v0, v0, v1
	v_add_f32_e32 v1, v216, v217
	v_add_f32_e32 v0, v0, v1
	v_add_f32_e32 v1, v218, v219
	v_add_f32_e32 v0, v1, v0
	v_fmamk_f32 v0, v0, 0x3c000000, v222
	v_rsq_f32_e32 v0, v0
	v_lshlrev_b32_e32 v1, 16, v252
	v_mul_f32_e32 v0, v85, v0
	v_mul_f32_e32 v0, v0, v1
	v_bfe_u32 v1, v0, 16, 1
	v_add3_u32 v0, v0, v1, s48
	ds_write_b16_d16_hi v214, v0 offset:41184
	v_add_f32_e32 v0, v228, v229
	v_add_f32_e32 v1, v230, v231
	v_add_f32_e32 v0, v0, v1
	v_add_f32_e32 v1, v232, v233
	v_add_f32_e32 v0, v0, v1
	v_add_f32_e32 v1, v234, v235
	v_add_f32_e32 v0, v1, v0
	v_fmamk_f32 v0, v0, 0x3c000000, v222
	v_rsq_f32_e32 v0, v0
	v_lshlrev_b32_e32 v1, 16, v253
	v_mul_f32_e32 v0, v86, v0
	v_mul_f32_e32 v0, v0, v1
	v_bfe_u32 v1, v0, 16, 1
	v_add3_u32 v0, v0, v1, s48
	ds_write_b16_d16_hi v214, v0 offset:41472
	v_add_f32_e32 v0, v236, v237
	v_add_f32_e32 v1, v238, v239
	v_add_f32_e32 v0, v0, v1
	v_add_f32_e32 v1, v240, v241
	v_add_f32_e32 v0, v0, v1
	v_add_f32_e32 v1, v242, v243
	v_add_f32_e32 v0, v1, v0
	v_fmamk_f32 v0, v0, 0x3c000000, v222
	v_rsq_f32_e32 v0, v0
	v_lshlrev_b32_e32 v1, 16, v92
	v_mul_f32_e32 v0, v87, v0
	v_mul_f32_e32 v0, v0, v1
	v_bfe_u32 v1, v0, 16, 1
	v_add3_u32 v0, v0, v1, s48
	ds_write_b16_d16_hi v214, v0 offset:41760
	s_cbranch_scc1 .LBB0_1797
	s_waitcnt vmcnt(0)
	v_add_f32_dpp v86, v51, v51 row_shr:1 row_mask:0xf bank_mask:0xf bound_ctrl:1
	v_add_f32_dpp v88, v45, v45 row_shr:1 row_mask:0xf bank_mask:0xf bound_ctrl:1
	v_add_f32_dpp v0, v48, v48 row_shr:1 row_mask:0xf bank_mask:0xf bound_ctrl:1
	v_add_f32_dpp v86, v86, v86 row_shr:2 row_mask:0xf bank_mask:0xf bound_ctrl:1
	v_add_f32_dpp v88, v88, v88 row_shr:2 row_mask:0xf bank_mask:0xf bound_ctrl:1
	v_add_f32_dpp v3, v49, v49 row_shr:1 row_mask:0xf bank_mask:0xf bound_ctrl:1
	v_add_f32_dpp v86, v86, v86 row_shr:4 row_mask:0xf bank_mask:0xf bound_ctrl:1
	v_add_f32_dpp v88, v88, v88 row_shr:4 row_mask:0xf bank_mask:0xf bound_ctrl:1
	v_add_f32_dpp v84, v50, v50 row_shr:1 row_mask:0xf bank_mask:0xf bound_ctrl:1
	v_add_f32_dpp v95, v86, v86 row_shr:8 row_mask:0xf bank_mask:0xf bound_ctrl:1
	v_add_f32_dpp v86, v44, v44 row_shr:1 row_mask:0xf bank_mask:0xf bound_ctrl:1
	v_add_f32_dpp v93, v88, v88 row_shr:8 row_mask:0xf bank_mask:0xf bound_ctrl:1
	v_add_f32_dpp v88, v46, v46 row_shr:1 row_mask:0xf bank_mask:0xf bound_ctrl:1
	v_add_f32_dpp v90, v47, v47 row_shr:1 row_mask:0xf bank_mask:0xf bound_ctrl:1
	v_add_f32_dpp v0, v0, v0 row_shr:2 row_mask:0xf bank_mask:0xf bound_ctrl:1
	v_add_f32_dpp v3, v3, v3 row_shr:2 row_mask:0xf bank_mask:0xf bound_ctrl:1
	v_add_f32_dpp v84, v84, v84 row_shr:2 row_mask:0xf bank_mask:0xf bound_ctrl:1
	v_add_f32_dpp v86, v86, v86 row_shr:2 row_mask:0xf bank_mask:0xf bound_ctrl:1
	v_add_f32_dpp v88, v88, v88 row_shr:2 row_mask:0xf bank_mask:0xf bound_ctrl:1
	v_add_f32_dpp v90, v90, v90 row_shr:2 row_mask:0xf bank_mask:0xf bound_ctrl:1
	v_add_f32_dpp v0, v0, v0 row_shr:4 row_mask:0xf bank_mask:0xf bound_ctrl:1
	v_add_f32_dpp v3, v3, v3 row_shr:4 row_mask:0xf bank_mask:0xf bound_ctrl:1
	v_add_f32_dpp v84, v84, v84 row_shr:4 row_mask:0xf bank_mask:0xf bound_ctrl:1
	v_add_f32_dpp v86, v86, v86 row_shr:4 row_mask:0xf bank_mask:0xf bound_ctrl:1
	v_add_f32_dpp v88, v88, v88 row_shr:4 row_mask:0xf bank_mask:0xf bound_ctrl:1
	v_add_f32_dpp v90, v90, v90 row_shr:4 row_mask:0xf bank_mask:0xf bound_ctrl:1
	s_waitcnt lgkmcnt(0)
	s_barrier
	s_cmp_lg_u32 s53, 0
	v_add_f32_dpp v0, v0, v0 row_shr:8 row_mask:0xf bank_mask:0xf bound_ctrl:1
	v_mov_b32_e32 v1, 0
	v_add_f32_dpp v3, v3, v3 row_shr:8 row_mask:0xf bank_mask:0xf bound_ctrl:1
	v_mov_b32_e32 v97, 0
	v_add_f32_dpp v84, v84, v84 row_shr:8 row_mask:0xf bank_mask:0xf bound_ctrl:1
	v_mov_b32_e32 v85, 0
	v_mov_b32_e32 v96, 0
	v_add_f32_dpp v86, v86, v86 row_shr:8 row_mask:0xf bank_mask:0xf bound_ctrl:1
	v_mov_b32_e32 v87, 0
	v_mov_b32_e32 v94, 0
	v_add_f32_dpp v88, v88, v88 row_shr:8 row_mask:0xf bank_mask:0xf bound_ctrl:1
	v_mov_b32_e32 v89, 0
	v_add_f32_dpp v91, v90, v90 row_shr:8 row_mask:0xf bank_mask:0xf bound_ctrl:1
	v_mov_b32_e32 v92, 0
	s_cselect_b64 s[0:1], -1, 0
	v_mov_b32_dpp v1, v0 row_bcast:15 row_mask:0xa bank_mask:0xf
	v_mov_b32_dpp v97, v3 row_bcast:15 row_mask:0xa bank_mask:0xf
	v_mov_b32_dpp v85, v84 row_bcast:15 row_mask:0xa bank_mask:0xf
	v_mov_b32_dpp v96, v95 row_bcast:15 row_mask:0xa bank_mask:0xf
	v_mov_b32_dpp v87, v86 row_bcast:15 row_mask:0xa bank_mask:0xf
	v_mov_b32_dpp v94, v93 row_bcast:15 row_mask:0xa bank_mask:0xf
	v_mov_b32_dpp v89, v88 row_bcast:15 row_mask:0xa bank_mask:0xf
	v_mov_b32_dpp v92, v91 row_bcast:15 row_mask:0xa bank_mask:0xf
	s_or_b64 s[50:51], s[18:19], s[0:1]
	s_and_saveexec_b64 s[0:1], s[50:51]
	s_cbranch_execz .LBB0_1815
	v_add_u32_e32 v90, s53, v210
	v_subrev_u32_e32 v90, 32, v90
	v_cndmask_b32_e64 v98, v90, v211, s[16:17]
	v_ashrrev_i32_e32 v99, 31, v98
	v_lshlrev_b64 v[98:99], 11, v[98:99]
	v_add_u32_e32 v90, v173, v176
	v_lshl_add_u64 v[102:103], v[178:179], 0, v[98:99]
	ds_read_b128 v[98:101], v90 offset:36864
	s_waitcnt lgkmcnt(0)
	global_store_dwordx4 v[102:103], v[98:101], off
